# P8: w2 fragment loads of steps 2 and 3 issued right after the previous step's MFMAs (ahead of the step's partial sums and GELU)
# baseline (speedup 1.0000x reference)
.LBB0_1000:
	v_lshl_add_u64 v[66:67], s[72:73], 0, v[54:55]
	v_add_co_u32_e32 v68, vcc, s60, v66
	v_lshl_add_u64 v[40:41], s[72:73], 0, v[52:53]
	s_nop 0
	v_addc_co_u32_e32 v69, vcc, 0, v67, vcc
	v_add_co_u32_e32 v70, vcc, s61, v40
	v_lshl_add_u64 v[38:39], v[66:67], 0, s[2:3]
	s_nop 0
	v_addc_co_u32_e32 v71, vcc, 0, v41, vcc
	global_load_dwordx4 v[34:37], v[68:69], off
	global_load_dwordx4 v[60:63], v[38:39], off offset:16
	v_lshl_add_u64 v[38:39], v[40:41], 0, s[4:5]
	global_load_dwordx4 v[78:81], v[70:71], off
	global_load_dwordx4 v[82:85], v[38:39], off offset:16
	v_add_co_u32_e32 v64, vcc, s62, v40
	v_lshl_add_u64 v[86:87], v[40:41], 0, s[16:17]
	s_nop 0
	v_addc_co_u32_e32 v65, vcc, 0, v41, vcc
	s_add_i32 s12, s12, -4
	v_lshl_add_u64 v[54:55], v[54:55], 0, s[54:55]
	v_lshl_add_u64 v[52:53], v[52:53], 0, s[54:55]
	s_cmp_eq_u32 s12, 0
	s_waitcnt vmcnt(1)
	v_pk_add_f32 v[38:39], v[36:37], v[80:81]
	s_waitcnt vmcnt(0)
	v_pk_add_f32 v[80:81], v[60:61], v[82:83]
	v_lshl_add_u64 v[60:61], v[40:41], 0, s[6:7]
	v_pk_add_f32 v[72:73], v[34:35], v[78:79]
	v_pk_add_f32 v[78:79], v[62:63], v[84:85]
	global_load_dwordx4 v[34:37], v[64:65], off
	s_nop 0
	global_load_dwordx4 v[60:63], v[60:61], off offset:16
	s_waitcnt vmcnt(1)
	v_pk_add_f32 v[38:39], v[38:39], v[36:37]
	s_waitcnt vmcnt(0)
	v_pk_add_f32 v[82:83], v[78:79], v[62:63]
	v_add_co_u32_e32 v62, vcc, s63, v40
	v_lshl_add_u64 v[78:79], v[40:41], 0, s[8:9]
	s_nop 0
	v_addc_co_u32_e32 v63, vcc, 0, v41, vcc
	v_pk_add_f32 v[72:73], v[72:73], v[34:35]
	v_pk_add_f32 v[60:61], v[80:81], v[60:61]
	global_load_dwordx4 v[34:37], v[62:63], off
	s_nop 0
	global_load_dwordx4 v[78:81], v[78:79], off offset:16
	s_waitcnt vmcnt(1)
	v_pk_add_f32 v[38:39], v[38:39], v[36:37]
	s_waitcnt vmcnt(0)
	v_pk_add_f32 v[84:85], v[60:61], v[78:79]
	v_add_co_u32_e32 v60, vcc, s64, v40
	v_lshl_add_u64 v[78:79], v[40:41], 0, s[10:11]
	s_nop 0
	v_addc_co_u32_e32 v61, vcc, 0, v41, vcc
	v_pk_add_f32 v[72:73], v[72:73], v[34:35]
	v_pk_add_f32 v[82:83], v[82:83], v[80:81]
	global_load_dwordx4 v[34:37], v[60:61], off
	s_nop 0
	global_load_dwordx4 v[78:81], v[78:79], off offset:16
	s_waitcnt vmcnt(1)
	v_pk_add_f32 v[34:35], v[72:73], v[34:35]
	s_nop 0
	v_mul_f32_e32 v49, 0x3d372713, v34
	v_mul_f32_e32 v49, v34, v49
	v_fma_f32 v49, v34, v49, v34
	v_mul_f32_e32 v49, 0x3fcc422a, v49
	s_waitcnt vmcnt(0)
	v_pk_add_f32 v[72:73], v[84:85], v[78:79]
	v_mul_f32_e32 v49, 0xbfb8aa3b, v49
	v_exp_f32_e32 v78, v49
	v_mul_f32_e32 v49, 0x3d372713, v72
	v_mul_f32_e32 v49, v72, v49
	v_fma_f32 v49, v72, v49, v72
	v_mul_f32_e32 v49, 0x3fcc422a, v49
	v_mul_f32_e32 v49, 0xbfb8aa3b, v49
	v_pk_add_f32 v[36:37], v[38:39], v[36:37]
	v_pk_add_f32 v[38:39], v[82:83], v[80:81]
	v_exp_f32_e32 v80, v49
	v_mul_f32_e32 v49, 0x3d372713, v35
	v_mul_f32_e32 v49, v35, v49
	v_fma_f32 v49, v35, v49, v35
	v_mul_f32_e32 v49, 0x3fcc422a, v49
	v_mul_f32_e32 v49, 0xbfb8aa3b, v49
	v_exp_f32_e32 v79, v49
	s_nop 0
	v_pk_add_f32 v[78:79], v[78:79], 1.0 op_sel_hi:[1,0]
	s_nop 0
	v_div_scale_f32 v49, s[66:67], v79, v79, 1.0
	v_rcp_f32_e32 v77, v49
	s_nop 0
	v_fma_f32 v81, -v49, v77, 1.0
	v_fmac_f32_e32 v77, v81, v77
	v_div_scale_f32 v81, vcc, 1.0, v79, 1.0
	v_mul_f32_e32 v82, v81, v77
	v_fma_f32 v83, -v49, v82, v81
	v_fmac_f32_e32 v82, v83, v77
	v_fma_f32 v49, -v49, v82, v81
	v_div_fmas_f32 v49, v49, v77, v82
	v_div_fixup_f32 v79, v49, v79, 1.0
	v_div_scale_f32 v49, s[66:67], v78, v78, 1.0
	v_rcp_f32_e32 v77, v49
	s_nop 0
	v_fma_f32 v81, -v49, v77, 1.0
	v_fmac_f32_e32 v77, v81, v77
	v_div_scale_f32 v81, vcc, 1.0, v78, 1.0
	v_mul_f32_e32 v82, v81, v77
	v_fma_f32 v83, -v49, v82, v81
	v_fmac_f32_e32 v82, v83, v77
	v_fma_f32 v49, -v49, v82, v81
	v_div_fmas_f32 v49, v49, v77, v82
	v_div_fixup_f32 v78, v49, v78, 1.0
	v_mul_f32_e32 v49, 0x3d372713, v73
	v_mul_f32_e32 v49, v73, v49
	v_fma_f32 v49, v73, v49, v73
	v_mul_f32_e32 v49, 0x3fcc422a, v49
	v_mul_f32_e32 v49, 0xbfb8aa3b, v49
	v_exp_f32_e32 v81, v49
	v_pk_mul_f32 v[34:35], v[34:35], v[78:79]
	v_pk_add_f32 v[78:79], v[80:81], 1.0 op_sel_hi:[1,0]
	s_nop 0
	v_div_scale_f32 v49, s[66:67], v79, v79, 1.0
	v_rcp_f32_e32 v77, v49
	v_cvt_pk_bf16_f32 v34, v34, v35
	v_fma_f32 v80, -v49, v77, 1.0
	v_fmac_f32_e32 v77, v80, v77
	v_div_scale_f32 v80, vcc, 1.0, v79, 1.0
	v_mul_f32_e32 v81, v80, v77
	v_fma_f32 v82, -v49, v81, v80
	v_fmac_f32_e32 v81, v82, v77
	v_fma_f32 v49, -v49, v81, v80
	v_div_fmas_f32 v49, v49, v77, v81
	v_div_fixup_f32 v79, v49, v79, 1.0
	v_div_scale_f32 v49, s[66:67], v78, v78, 1.0
	v_rcp_f32_e32 v77, v49
	s_nop 0
	v_fma_f32 v80, -v49, v77, 1.0
	v_fmac_f32_e32 v77, v80, v77
	v_div_scale_f32 v80, vcc, 1.0, v78, 1.0
	v_mul_f32_e32 v81, v80, v77
	v_fma_f32 v82, -v49, v81, v80
	v_fmac_f32_e32 v81, v82, v77
	v_fma_f32 v49, -v49, v81, v80
	v_div_fmas_f32 v49, v49, v77, v81
	v_div_fixup_f32 v78, v49, v78, 1.0
	v_mul_f32_e32 v49, 0x3d372713, v36
	v_mul_f32_e32 v49, v36, v49
	v_fma_f32 v49, v36, v49, v36
	v_mul_f32_e32 v49, 0x3fcc422a, v49
	v_mul_f32_e32 v49, 0xbfb8aa3b, v49
	v_pk_mul_f32 v[72:73], v[72:73], v[78:79]
	v_exp_f32_e32 v78, v49
	v_mul_f32_e32 v49, 0x3d372713, v38
	v_mul_f32_e32 v49, v38, v49
	v_fma_f32 v49, v38, v49, v38
	v_mul_f32_e32 v49, 0x3fcc422a, v49
	v_mul_f32_e32 v49, 0xbfb8aa3b, v49
	v_exp_f32_e32 v80, v49
	v_mul_f32_e32 v49, 0x3d372713, v37
	v_mul_f32_e32 v49, v37, v49
	v_fma_f32 v49, v37, v49, v37
	v_mul_f32_e32 v49, 0x3fcc422a, v49
	v_mul_f32_e32 v49, 0xbfb8aa3b, v49
	v_exp_f32_e32 v79, v49
	s_nop 0
	v_pk_add_f32 v[78:79], v[78:79], 1.0 op_sel_hi:[1,0]
	s_nop 0
	v_div_scale_f32 v49, s[66:67], v79, v79, 1.0
	v_rcp_f32_e32 v77, v49
	s_nop 0
	v_fma_f32 v81, -v49, v77, 1.0
	v_fmac_f32_e32 v77, v81, v77
	v_div_scale_f32 v81, vcc, 1.0, v79, 1.0
	v_mul_f32_e32 v82, v81, v77
	v_fma_f32 v83, -v49, v82, v81
	v_fmac_f32_e32 v82, v83, v77
	v_fma_f32 v49, -v49, v82, v81
	v_div_fmas_f32 v49, v49, v77, v82
	v_div_fixup_f32 v79, v49, v79, 1.0
	v_div_scale_f32 v49, s[66:67], v78, v78, 1.0
	v_rcp_f32_e32 v77, v49
	s_nop 0
	v_fma_f32 v81, -v49, v77, 1.0
	v_fmac_f32_e32 v77, v81, v77
	v_div_scale_f32 v81, vcc, 1.0, v78, 1.0
	v_mul_f32_e32 v82, v81, v77
	v_fma_f32 v83, -v49, v82, v81
	v_fmac_f32_e32 v82, v83, v77
	v_fma_f32 v49, -v49, v82, v81
	v_div_fmas_f32 v49, v49, v77, v82
	v_div_fixup_f32 v78, v49, v78, 1.0
	v_mul_f32_e32 v49, 0x3d372713, v39
	v_mul_f32_e32 v49, v39, v49
	v_fma_f32 v49, v39, v49, v39
	v_mul_f32_e32 v49, 0x3fcc422a, v49
	v_mul_f32_e32 v49, 0xbfb8aa3b, v49
	v_exp_f32_e32 v81, v49
	v_pk_mul_f32 v[36:37], v[36:37], v[78:79]
	v_pk_add_f32 v[78:79], v[80:81], 1.0 op_sel_hi:[1,0]
	s_nop 0
	v_div_scale_f32 v49, s[66:67], v79, v79, 1.0
	v_rcp_f32_e32 v77, v49
	v_cvt_pk_bf16_f32 v35, v36, v37
	v_cvt_pk_bf16_f32 v36, v72, v73
	v_lshl_add_u64 v[72:73], s[72:73], 0, v[58:59]
	v_fma_f32 v80, -v49, v77, 1.0
	v_fmac_f32_e32 v77, v80, v77
	v_div_scale_f32 v80, vcc, 1.0, v79, 1.0
	v_mul_f32_e32 v81, v80, v77
	v_fma_f32 v82, -v49, v81, v80
	v_fmac_f32_e32 v81, v82, v77
	v_fma_f32 v49, -v49, v81, v80
	v_div_fmas_f32 v49, v49, v77, v81
	v_div_fixup_f32 v79, v49, v79, 1.0
	v_div_scale_f32 v49, s[66:67], v78, v78, 1.0
	v_rcp_f32_e32 v77, v49
	v_lshl_add_u64 v[58:59], v[58:59], 0, s[56:57]
	v_fma_f32 v80, -v49, v77, 1.0
	v_fmac_f32_e32 v77, v80, v77
	v_div_scale_f32 v80, vcc, 1.0, v78, 1.0
	v_mul_f32_e32 v81, v80, v77
	v_fma_f32 v82, -v49, v81, v80
	v_fmac_f32_e32 v81, v82, v77
	v_fma_f32 v49, -v49, v81, v80
	v_div_fmas_f32 v49, v49, v77, v81
	v_div_fixup_f32 v78, v49, v78, 1.0
	v_pk_mul_f32 v[38:39], v[38:39], v[78:79]
	global_load_dwordx4 v[78:81], v[72:73], off offset:-64
	v_cvt_pk_bf16_f32 v37, v38, v39
	v_lshl_add_u64 v[38:39], s[72:73], 0, v[56:57]
	v_lshl_add_u64 v[56:57], v[56:57], 0, s[56:57]
	global_load_dwordx4 v[140:143], v[38:39], off offset:-64
	s_waitcnt vmcnt(1)
	v_mfma_f32_32x32x16_bf16 v[2:17], v[78:81], v[34:37], v[2:17]
	s_waitcnt vmcnt(0)
	v_mfma_f32_32x32x16_bf16 v[18:33], v[140:143], v[34:37], v[18:33]
	global_load_dwordx4 v[144:147], v[72:73], off offset:-32
	global_load_dwordx4 v[148:151], v[38:39], off offset:-32
	v_lshl_add_u64 v[78:79], v[66:67], 0, s[14:15]
	global_load_dwordx4 v[34:37], v[68:69], off offset:64
	s_nop 0
	global_load_dwordx4 v[78:81], v[78:79], off offset:16
	s_nop 0
	global_load_dwordx4 v[82:85], v[70:71], off offset:64
	s_nop 0
	global_load_dwordx4 v[86:89], v[86:87], off offset:16
	s_waitcnt vmcnt(1)
	v_pk_add_f32 v[84:85], v[36:37], v[84:85]
	s_waitcnt vmcnt(0)
	v_pk_add_f32 v[86:87], v[78:79], v[86:87]
	v_lshl_add_u64 v[78:79], v[40:41], 0, s[18:19]
	v_pk_add_f32 v[82:83], v[34:35], v[82:83]
	v_pk_add_f32 v[88:89], v[80:81], v[88:89]
	global_load_dwordx4 v[34:37], v[64:65], off offset:64
	s_nop 0
	global_load_dwordx4 v[78:81], v[78:79], off offset:16
	s_waitcnt vmcnt(1)
	v_pk_add_f32 v[84:85], v[84:85], v[36:37]
	s_waitcnt vmcnt(0)
	v_pk_add_f32 v[86:87], v[86:87], v[78:79]
	v_lshl_add_u64 v[78:79], v[40:41], 0, s[20:21]
	v_pk_add_f32 v[82:83], v[82:83], v[34:35]
	v_pk_add_f32 v[88:89], v[88:89], v[80:81]
	global_load_dwordx4 v[34:37], v[62:63], off offset:64
	s_nop 0
	global_load_dwordx4 v[78:81], v[78:79], off offset:16
	s_waitcnt vmcnt(1)
	v_pk_add_f32 v[84:85], v[84:85], v[36:37]
	s_waitcnt vmcnt(0)
	v_pk_add_f32 v[86:87], v[86:87], v[78:79]
	v_lshl_add_u64 v[78:79], v[40:41], 0, s[22:23]
	v_pk_add_f32 v[82:83], v[82:83], v[34:35]
	v_pk_add_f32 v[88:89], v[88:89], v[80:81]
	global_load_dwordx4 v[34:37], v[60:61], off offset:64
	s_nop 0
	global_load_dwordx4 v[78:81], v[78:79], off offset:16
	s_waitcnt vmcnt(1)
	v_pk_add_f32 v[34:35], v[82:83], v[34:35]
	s_nop 0
	v_mul_f32_e32 v49, 0x3d372713, v34
	v_mul_f32_e32 v49, v34, v49
	v_fma_f32 v49, v34, v49, v34
	v_mul_f32_e32 v49, 0x3fcc422a, v49
	s_waitcnt vmcnt(0)
	v_pk_add_f32 v[78:79], v[86:87], v[78:79]
	v_mul_f32_e32 v49, 0xbfb8aa3b, v49
	v_exp_f32_e32 v82, v49
	v_mul_f32_e32 v49, 0x3d372713, v78
	v_mul_f32_e32 v49, v78, v49
	v_fma_f32 v49, v78, v49, v78
	v_mul_f32_e32 v49, 0x3fcc422a, v49
	v_mul_f32_e32 v49, 0xbfb8aa3b, v49
	v_pk_add_f32 v[36:37], v[84:85], v[36:37]
	v_exp_f32_e32 v84, v49
	v_mul_f32_e32 v49, 0x3d372713, v35
	v_mul_f32_e32 v49, v35, v49
	v_fma_f32 v49, v35, v49, v35
	v_mul_f32_e32 v49, 0x3fcc422a, v49
	v_mul_f32_e32 v49, 0xbfb8aa3b, v49
	v_exp_f32_e32 v83, v49
	v_pk_add_f32 v[80:81], v[88:89], v[80:81]
	v_pk_add_f32 v[82:83], v[82:83], 1.0 op_sel_hi:[1,0]
	s_nop 0
	v_div_scale_f32 v49, s[66:67], v83, v83, 1.0
	v_rcp_f32_e32 v77, v49
	s_nop 0
	v_fma_f32 v85, -v49, v77, 1.0
	v_fmac_f32_e32 v77, v85, v77
	v_div_scale_f32 v85, vcc, 1.0, v83, 1.0
	v_mul_f32_e32 v86, v85, v77
	v_fma_f32 v87, -v49, v86, v85
	v_fmac_f32_e32 v86, v87, v77
	v_fma_f32 v49, -v49, v86, v85
	v_div_fmas_f32 v49, v49, v77, v86
	v_div_fixup_f32 v83, v49, v83, 1.0
	v_div_scale_f32 v49, s[66:67], v82, v82, 1.0
	v_rcp_f32_e32 v77, v49
	s_nop 0
	v_fma_f32 v85, -v49, v77, 1.0
	v_fmac_f32_e32 v77, v85, v77
	v_div_scale_f32 v85, vcc, 1.0, v82, 1.0
	v_mul_f32_e32 v86, v85, v77
	v_fma_f32 v87, -v49, v86, v85
	v_fmac_f32_e32 v86, v87, v77
	v_fma_f32 v49, -v49, v86, v85
	v_div_fmas_f32 v49, v49, v77, v86
	v_div_fixup_f32 v82, v49, v82, 1.0
	v_mul_f32_e32 v49, 0x3d372713, v79
	v_mul_f32_e32 v49, v79, v49
	v_fma_f32 v49, v79, v49, v79
	v_mul_f32_e32 v49, 0x3fcc422a, v49
	v_mul_f32_e32 v49, 0xbfb8aa3b, v49
	v_exp_f32_e32 v85, v49
	v_pk_mul_f32 v[34:35], v[34:35], v[82:83]
	v_pk_add_f32 v[82:83], v[84:85], 1.0 op_sel_hi:[1,0]
	s_nop 0
	v_div_scale_f32 v49, s[66:67], v83, v83, 1.0
	v_rcp_f32_e32 v77, v49
	v_cvt_pk_bf16_f32 v34, v34, v35
	v_fma_f32 v84, -v49, v77, 1.0
	v_fmac_f32_e32 v77, v84, v77
	v_div_scale_f32 v84, vcc, 1.0, v83, 1.0
	v_mul_f32_e32 v85, v84, v77
	v_fma_f32 v86, -v49, v85, v84
	v_fmac_f32_e32 v85, v86, v77
	v_fma_f32 v49, -v49, v85, v84
	v_div_fmas_f32 v49, v49, v77, v85
	v_div_fixup_f32 v83, v49, v83, 1.0
	v_div_scale_f32 v49, s[66:67], v82, v82, 1.0
	v_rcp_f32_e32 v77, v49
	s_nop 0
	v_fma_f32 v84, -v49, v77, 1.0
	v_fmac_f32_e32 v77, v84, v77
	v_div_scale_f32 v84, vcc, 1.0, v82, 1.0
	v_mul_f32_e32 v85, v84, v77
	v_fma_f32 v86, -v49, v85, v84
	v_fmac_f32_e32 v85, v86, v77
	v_fma_f32 v49, -v49, v85, v84
	v_div_fmas_f32 v49, v49, v77, v85
	v_div_fixup_f32 v82, v49, v82, 1.0
	v_mul_f32_e32 v49, 0x3d372713, v36
	v_mul_f32_e32 v49, v36, v49
	v_fma_f32 v49, v36, v49, v36
	v_mul_f32_e32 v49, 0x3fcc422a, v49
	v_mul_f32_e32 v49, 0xbfb8aa3b, v49
	v_pk_mul_f32 v[78:79], v[78:79], v[82:83]
	v_exp_f32_e32 v82, v49
	v_mul_f32_e32 v49, 0x3d372713, v80
	v_mul_f32_e32 v49, v80, v49
	v_fma_f32 v49, v80, v49, v80
	v_mul_f32_e32 v49, 0x3fcc422a, v49
	v_mul_f32_e32 v49, 0xbfb8aa3b, v49
	v_exp_f32_e32 v84, v49
	v_mul_f32_e32 v49, 0x3d372713, v37
	v_mul_f32_e32 v49, v37, v49
	v_fma_f32 v49, v37, v49, v37
	v_mul_f32_e32 v49, 0x3fcc422a, v49
	v_mul_f32_e32 v49, 0xbfb8aa3b, v49
	v_exp_f32_e32 v83, v49
	s_nop 0
	v_pk_add_f32 v[82:83], v[82:83], 1.0 op_sel_hi:[1,0]
	s_nop 0
	v_div_scale_f32 v49, s[66:67], v83, v83, 1.0
	v_rcp_f32_e32 v77, v49
	s_nop 0
	v_fma_f32 v85, -v49, v77, 1.0
	v_fmac_f32_e32 v77, v85, v77
	v_div_scale_f32 v85, vcc, 1.0, v83, 1.0
	v_mul_f32_e32 v86, v85, v77
	v_fma_f32 v87, -v49, v86, v85
	v_fmac_f32_e32 v86, v87, v77
	v_fma_f32 v49, -v49, v86, v85
	v_div_fmas_f32 v49, v49, v77, v86
	v_div_fixup_f32 v83, v49, v83, 1.0
	v_div_scale_f32 v49, s[66:67], v82, v82, 1.0
	v_rcp_f32_e32 v77, v49
	s_nop 0
	v_fma_f32 v85, -v49, v77, 1.0
	v_fmac_f32_e32 v77, v85, v77
	v_div_scale_f32 v85, vcc, 1.0, v82, 1.0
	v_mul_f32_e32 v86, v85, v77
	v_fma_f32 v87, -v49, v86, v85
	v_fmac_f32_e32 v86, v87, v77
	v_fma_f32 v49, -v49, v86, v85
	v_div_fmas_f32 v49, v49, v77, v86
	v_div_fixup_f32 v82, v49, v82, 1.0
	v_mul_f32_e32 v49, 0x3d372713, v81
	v_mul_f32_e32 v49, v81, v49
	v_fma_f32 v49, v81, v49, v81
	v_mul_f32_e32 v49, 0x3fcc422a, v49
	v_mul_f32_e32 v49, 0xbfb8aa3b, v49
	v_exp_f32_e32 v85, v49
	v_pk_mul_f32 v[36:37], v[36:37], v[82:83]
	v_pk_add_f32 v[82:83], v[84:85], 1.0 op_sel_hi:[1,0]
	s_nop 0
	v_div_scale_f32 v49, s[66:67], v83, v83, 1.0
	v_rcp_f32_e32 v77, v49
	v_cvt_pk_bf16_f32 v35, v36, v37
	v_cvt_pk_bf16_f32 v36, v78, v79
	v_fma_f32 v84, -v49, v77, 1.0
	v_fmac_f32_e32 v77, v84, v77
	v_div_scale_f32 v84, vcc, 1.0, v83, 1.0
	v_mul_f32_e32 v85, v84, v77
	v_fma_f32 v86, -v49, v85, v84
	v_fmac_f32_e32 v85, v86, v77
	v_fma_f32 v49, -v49, v85, v84
	v_div_fmas_f32 v49, v49, v77, v85
	v_div_fixup_f32 v83, v49, v83, 1.0
	v_div_scale_f32 v49, s[66:67], v82, v82, 1.0
	v_rcp_f32_e32 v77, v49
	s_nop 0
	v_fma_f32 v84, -v49, v77, 1.0
	v_fmac_f32_e32 v77, v84, v77
	v_div_scale_f32 v84, vcc, 1.0, v82, 1.0
	v_mul_f32_e32 v85, v84, v77
	v_fma_f32 v86, -v49, v85, v84
	v_fmac_f32_e32 v85, v86, v77
	v_fma_f32 v49, -v49, v85, v84
	v_div_fmas_f32 v49, v49, v77, v85
	v_div_fixup_f32 v82, v49, v82, 1.0
	v_pk_mul_f32 v[80:81], v[80:81], v[82:83]
	v_lshl_add_u64 v[86:87], v[40:41], 0, s[26:27]
	v_cvt_pk_bf16_f32 v37, v80, v81
	s_nop 1
	v_mfma_f32_32x32x16_bf16 v[2:17], v[144:147], v[34:37], v[2:17]
	v_mfma_f32_32x32x16_bf16 v[18:33], v[148:151], v[34:37], v[18:33]
	global_load_dwordx4 v[152:155], v[72:73], off
	global_load_dwordx4 v[156:159], v[38:39], off
	v_lshl_add_u64 v[78:79], v[66:67], 0, s[24:25]
	global_load_dwordx4 v[34:37], v[68:69], off offset:128
	s_nop 0
	global_load_dwordx4 v[78:81], v[78:79], off offset:16
	s_nop 0
	global_load_dwordx4 v[82:85], v[70:71], off offset:128
	s_nop 0
	global_load_dwordx4 v[86:89], v[86:87], off offset:16
	v_lshl_add_u64 v[66:67], v[66:67], 0, s[36:37]
	s_waitcnt vmcnt(1)
	v_pk_add_f32 v[84:85], v[36:37], v[84:85]
	s_waitcnt vmcnt(0)
	v_pk_add_f32 v[86:87], v[78:79], v[86:87]
	v_lshl_add_u64 v[78:79], v[40:41], 0, s[28:29]
	v_pk_add_f32 v[82:83], v[34:35], v[82:83]
	v_pk_add_f32 v[88:89], v[80:81], v[88:89]
	global_load_dwordx4 v[34:37], v[64:65], off offset:128
	s_nop 0
	global_load_dwordx4 v[78:81], v[78:79], off offset:16
	s_waitcnt vmcnt(1)
	v_pk_add_f32 v[84:85], v[84:85], v[36:37]
	s_waitcnt vmcnt(0)
	v_pk_add_f32 v[86:87], v[86:87], v[78:79]
	v_lshl_add_u64 v[78:79], v[40:41], 0, s[30:31]
	v_pk_add_f32 v[82:83], v[82:83], v[34:35]
	v_pk_add_f32 v[88:89], v[88:89], v[80:81]
	global_load_dwordx4 v[34:37], v[62:63], off offset:128
	s_nop 0
	global_load_dwordx4 v[78:81], v[78:79], off offset:16
	s_waitcnt vmcnt(1)
	v_pk_add_f32 v[84:85], v[84:85], v[36:37]
	s_waitcnt vmcnt(0)
	v_pk_add_f32 v[86:87], v[86:87], v[78:79]
	v_lshl_add_u64 v[78:79], v[40:41], 0, s[34:35]
	v_pk_add_f32 v[82:83], v[82:83], v[34:35]
	v_pk_add_f32 v[88:89], v[88:89], v[80:81]
	global_load_dwordx4 v[34:37], v[60:61], off offset:128
	s_nop 0
	global_load_dwordx4 v[78:81], v[78:79], off offset:16
	s_waitcnt vmcnt(1)
	v_pk_add_f32 v[34:35], v[82:83], v[34:35]
	s_nop 0
	v_mul_f32_e32 v49, 0x3d372713, v34
	v_mul_f32_e32 v49, v34, v49
	v_fma_f32 v49, v34, v49, v34
	v_mul_f32_e32 v49, 0x3fcc422a, v49
	s_waitcnt vmcnt(0)
	v_pk_add_f32 v[78:79], v[86:87], v[78:79]
	v_mul_f32_e32 v49, 0xbfb8aa3b, v49
	v_exp_f32_e32 v82, v49
	v_mul_f32_e32 v49, 0x3d372713, v78
	v_mul_f32_e32 v49, v78, v49
	v_fma_f32 v49, v78, v49, v78
	v_mul_f32_e32 v49, 0x3fcc422a, v49
	v_mul_f32_e32 v49, 0xbfb8aa3b, v49
	v_pk_add_f32 v[36:37], v[84:85], v[36:37]
	v_exp_f32_e32 v84, v49
	v_mul_f32_e32 v49, 0x3d372713, v35
	v_mul_f32_e32 v49, v35, v49
	v_fma_f32 v49, v35, v49, v35
	v_mul_f32_e32 v49, 0x3fcc422a, v49
	v_mul_f32_e32 v49, 0xbfb8aa3b, v49
	v_exp_f32_e32 v83, v49
	v_pk_add_f32 v[80:81], v[88:89], v[80:81]
	v_pk_add_f32 v[82:83], v[82:83], 1.0 op_sel_hi:[1,0]
	s_nop 0
	v_div_scale_f32 v49, s[66:67], v83, v83, 1.0
	v_rcp_f32_e32 v77, v49
	s_nop 0
	v_fma_f32 v85, -v49, v77, 1.0
	v_fmac_f32_e32 v77, v85, v77
	v_div_scale_f32 v85, vcc, 1.0, v83, 1.0
	v_mul_f32_e32 v86, v85, v77
	v_fma_f32 v87, -v49, v86, v85
	v_fmac_f32_e32 v86, v87, v77
	v_fma_f32 v49, -v49, v86, v85
	v_div_fmas_f32 v49, v49, v77, v86
	v_div_fixup_f32 v83, v49, v83, 1.0
	v_div_scale_f32 v49, s[66:67], v82, v82, 1.0
	v_rcp_f32_e32 v77, v49
	s_nop 0
	v_fma_f32 v85, -v49, v77, 1.0
	v_fmac_f32_e32 v77, v85, v77
	v_div_scale_f32 v85, vcc, 1.0, v82, 1.0
	v_mul_f32_e32 v86, v85, v77
	v_fma_f32 v87, -v49, v86, v85
	v_fmac_f32_e32 v86, v87, v77
	v_fma_f32 v49, -v49, v86, v85
	v_div_fmas_f32 v49, v49, v77, v86
	v_div_fixup_f32 v82, v49, v82, 1.0
	v_mul_f32_e32 v49, 0x3d372713, v79
	v_mul_f32_e32 v49, v79, v49
	v_fma_f32 v49, v79, v49, v79
	v_mul_f32_e32 v49, 0x3fcc422a, v49
	v_mul_f32_e32 v49, 0xbfb8aa3b, v49
	v_exp_f32_e32 v85, v49
	v_pk_mul_f32 v[34:35], v[34:35], v[82:83]
	v_pk_add_f32 v[82:83], v[84:85], 1.0 op_sel_hi:[1,0]
	s_nop 0
	v_div_scale_f32 v49, s[66:67], v83, v83, 1.0
	v_rcp_f32_e32 v77, v49
	v_cvt_pk_bf16_f32 v34, v34, v35
	v_fma_f32 v84, -v49, v77, 1.0
	v_fmac_f32_e32 v77, v84, v77
	v_div_scale_f32 v84, vcc, 1.0, v83, 1.0
	v_mul_f32_e32 v85, v84, v77
	v_fma_f32 v86, -v49, v85, v84
	v_fmac_f32_e32 v85, v86, v77
	v_fma_f32 v49, -v49, v85, v84
	v_div_fmas_f32 v49, v49, v77, v85
	v_div_fixup_f32 v83, v49, v83, 1.0
	v_div_scale_f32 v49, s[66:67], v82, v82, 1.0
	v_rcp_f32_e32 v77, v49
	s_nop 0
	v_fma_f32 v84, -v49, v77, 1.0
	v_fmac_f32_e32 v77, v84, v77
	v_div_scale_f32 v84, vcc, 1.0, v82, 1.0
	v_mul_f32_e32 v85, v84, v77
	v_fma_f32 v86, -v49, v85, v84
	v_fmac_f32_e32 v85, v86, v77
	v_fma_f32 v49, -v49, v85, v84
	v_div_fmas_f32 v49, v49, v77, v85
	v_div_fixup_f32 v82, v49, v82, 1.0
	v_mul_f32_e32 v49, 0x3d372713, v36
	v_mul_f32_e32 v49, v36, v49
	v_fma_f32 v49, v36, v49, v36
	v_mul_f32_e32 v49, 0x3fcc422a, v49
	v_mul_f32_e32 v49, 0xbfb8aa3b, v49
	v_pk_mul_f32 v[78:79], v[78:79], v[82:83]
	v_exp_f32_e32 v82, v49
	v_mul_f32_e32 v49, 0x3d372713, v80
	v_mul_f32_e32 v49, v80, v49
	v_fma_f32 v49, v80, v49, v80
	v_mul_f32_e32 v49, 0x3fcc422a, v49
	v_mul_f32_e32 v49, 0xbfb8aa3b, v49
	v_exp_f32_e32 v84, v49
	v_mul_f32_e32 v49, 0x3d372713, v37
	v_mul_f32_e32 v49, v37, v49
	v_fma_f32 v49, v37, v49, v37
	v_mul_f32_e32 v49, 0x3fcc422a, v49
	v_mul_f32_e32 v49, 0xbfb8aa3b, v49
	v_exp_f32_e32 v83, v49
	s_nop 0
	v_pk_add_f32 v[82:83], v[82:83], 1.0 op_sel_hi:[1,0]
	s_nop 0
	v_div_scale_f32 v49, s[66:67], v83, v83, 1.0
	v_rcp_f32_e32 v77, v49
	s_nop 0
	v_fma_f32 v85, -v49, v77, 1.0
	v_fmac_f32_e32 v77, v85, v77
	v_div_scale_f32 v85, vcc, 1.0, v83, 1.0
	v_mul_f32_e32 v86, v85, v77
	v_fma_f32 v87, -v49, v86, v85
	v_fmac_f32_e32 v86, v87, v77
	v_fma_f32 v49, -v49, v86, v85
	v_div_fmas_f32 v49, v49, v77, v86
	v_div_fixup_f32 v83, v49, v83, 1.0
	v_div_scale_f32 v49, s[66:67], v82, v82, 1.0
	v_rcp_f32_e32 v77, v49
	s_nop 0
	v_fma_f32 v85, -v49, v77, 1.0
	v_fmac_f32_e32 v77, v85, v77
	v_div_scale_f32 v85, vcc, 1.0, v82, 1.0
	v_mul_f32_e32 v86, v85, v77
	v_fma_f32 v87, -v49, v86, v85
	v_fmac_f32_e32 v86, v87, v77
	v_fma_f32 v49, -v49, v86, v85
	v_div_fmas_f32 v49, v49, v77, v86
	v_div_fixup_f32 v82, v49, v82, 1.0
	v_mul_f32_e32 v49, 0x3d372713, v81
	v_mul_f32_e32 v49, v81, v49
	v_fma_f32 v49, v81, v49, v81
	v_mul_f32_e32 v49, 0x3fcc422a, v49
	v_mul_f32_e32 v49, 0xbfb8aa3b, v49
	v_exp_f32_e32 v85, v49
	v_pk_mul_f32 v[36:37], v[36:37], v[82:83]
	v_pk_add_f32 v[82:83], v[84:85], 1.0 op_sel_hi:[1,0]
	s_nop 0
	v_div_scale_f32 v49, s[66:67], v83, v83, 1.0
	v_rcp_f32_e32 v77, v49
	v_cvt_pk_bf16_f32 v35, v36, v37
	v_cvt_pk_bf16_f32 v36, v78, v79
	v_fma_f32 v84, -v49, v77, 1.0
	v_fmac_f32_e32 v77, v84, v77
	v_div_scale_f32 v84, vcc, 1.0, v83, 1.0
	v_mul_f32_e32 v85, v84, v77
	v_fma_f32 v86, -v49, v85, v84
	v_fmac_f32_e32 v85, v86, v77
	v_fma_f32 v49, -v49, v85, v84
	v_div_fmas_f32 v49, v49, v77, v85
	v_div_fixup_f32 v83, v49, v83, 1.0
	v_div_scale_f32 v49, s[66:67], v82, v82, 1.0
	v_rcp_f32_e32 v77, v49
	s_nop 0
	v_fma_f32 v84, -v49, v77, 1.0
	v_fmac_f32_e32 v77, v84, v77
	v_div_scale_f32 v84, vcc, 1.0, v82, 1.0
	v_mul_f32_e32 v85, v84, v77
	v_fma_f32 v86, -v49, v85, v84
	v_fmac_f32_e32 v85, v86, v77
	v_fma_f32 v49, -v49, v85, v84
	v_div_fmas_f32 v49, v49, v77, v85
	v_div_fixup_f32 v82, v49, v82, 1.0
	v_pk_mul_f32 v[80:81], v[80:81], v[82:83]
	v_lshl_add_u64 v[82:83], v[40:41], 0, s[40:41]
	v_cvt_pk_bf16_f32 v37, v80, v81
	s_nop 1
	v_mfma_f32_32x32x16_bf16 v[2:17], v[152:155], v[34:37], v[2:17]
	v_mfma_f32_32x32x16_bf16 v[18:33], v[156:159], v[34:37], v[18:33]
	global_load_dwordx4 v[34:37], v[68:69], off offset:192
	s_nop 0
	global_load_dwordx4 v[66:69], v[66:67], off offset:16
	s_nop 0
	global_load_dwordx4 v[78:81], v[70:71], off offset:192
	s_nop 0
	global_load_dwordx4 v[82:85], v[82:83], off offset:16
	s_waitcnt vmcnt(1)
	v_pk_add_f32 v[70:71], v[36:37], v[80:81]
	s_waitcnt vmcnt(0)
	v_pk_add_f32 v[80:81], v[66:67], v[82:83]
	v_lshl_add_u64 v[66:67], v[40:41], 0, s[46:47]
	v_pk_add_f32 v[78:79], v[34:35], v[78:79]
	global_load_dwordx4 v[34:37], v[64:65], off offset:192
	s_nop 0
	global_load_dwordx4 v[64:67], v[66:67], off offset:16
	v_pk_add_f32 v[68:69], v[68:69], v[84:85]
	s_waitcnt vmcnt(1)
	v_pk_add_f32 v[70:71], v[70:71], v[36:37]
	s_waitcnt vmcnt(0)
	v_pk_add_f32 v[66:67], v[68:69], v[66:67]
	v_pk_add_f32 v[68:69], v[80:81], v[64:65]
	v_lshl_add_u64 v[64:65], v[40:41], 0, s[50:51]
	v_pk_add_f32 v[78:79], v[78:79], v[34:35]
	global_load_dwordx4 v[34:37], v[62:63], off offset:192
	s_nop 0
	global_load_dwordx4 v[62:65], v[64:65], off offset:16
	v_lshl_add_u64 v[40:41], v[40:41], 0, s[52:53]
	s_waitcnt vmcnt(1)
	v_pk_add_f32 v[70:71], v[70:71], v[36:37]
	v_pk_add_f32 v[78:79], v[78:79], v[34:35]
	s_waitcnt vmcnt(0)
	v_pk_add_f32 v[64:65], v[66:67], v[64:65]
	v_pk_add_f32 v[66:67], v[68:69], v[62:63]
	global_load_dwordx4 v[34:37], v[60:61], off offset:192
	s_nop 0
	global_load_dwordx4 v[60:63], v[40:41], off offset:16
	s_waitcnt vmcnt(1)
	v_pk_add_f32 v[34:35], v[78:79], v[34:35]
	s_nop 0
	v_mul_f32_e32 v49, 0x3d372713, v34
	v_mul_f32_e32 v49, v34, v49
	v_fma_f32 v49, v34, v49, v34
	v_mul_f32_e32 v49, 0x3fcc422a, v49
	s_waitcnt vmcnt(0)
	v_pk_add_f32 v[60:61], v[66:67], v[60:61]
	v_mul_f32_e32 v49, 0xbfb8aa3b, v49
	v_pk_add_f32 v[40:41], v[64:65], v[62:63]
	v_exp_f32_e32 v62, v49
	v_mul_f32_e32 v49, 0x3d372713, v60
	v_mul_f32_e32 v49, v60, v49
	v_fma_f32 v49, v60, v49, v60
	v_mul_f32_e32 v49, 0x3fcc422a, v49
	v_mul_f32_e32 v49, 0xbfb8aa3b, v49
	v_exp_f32_e32 v64, v49
	v_mul_f32_e32 v49, 0x3d372713, v35
	v_mul_f32_e32 v49, v35, v49
	v_fma_f32 v49, v35, v49, v35
	v_mul_f32_e32 v49, 0x3fcc422a, v49
	v_mul_f32_e32 v49, 0xbfb8aa3b, v49
	v_exp_f32_e32 v63, v49
	v_pk_add_f32 v[36:37], v[70:71], v[36:37]
	v_pk_add_f32 v[62:63], v[62:63], 1.0 op_sel_hi:[1,0]
	s_nop 0
	v_div_scale_f32 v49, s[66:67], v63, v63, 1.0
	v_rcp_f32_e32 v65, v49
	s_nop 0
	v_fma_f32 v66, -v49, v65, 1.0
	v_fmac_f32_e32 v65, v66, v65
	v_div_scale_f32 v66, vcc, 1.0, v63, 1.0
	v_mul_f32_e32 v67, v66, v65
	v_fma_f32 v68, -v49, v67, v66
	v_fmac_f32_e32 v67, v68, v65
	v_fma_f32 v49, -v49, v67, v66
	v_div_fmas_f32 v49, v49, v65, v67
	v_div_fixup_f32 v63, v49, v63, 1.0
	v_div_scale_f32 v49, s[66:67], v62, v62, 1.0
	v_rcp_f32_e32 v65, v49
	s_nop 0
	v_fma_f32 v66, -v49, v65, 1.0
	v_fmac_f32_e32 v65, v66, v65
	v_div_scale_f32 v66, vcc, 1.0, v62, 1.0
	v_mul_f32_e32 v67, v66, v65
	v_fma_f32 v68, -v49, v67, v66
	v_fmac_f32_e32 v67, v68, v65
	v_fma_f32 v49, -v49, v67, v66
	v_div_fmas_f32 v49, v49, v65, v67
	v_div_fixup_f32 v62, v49, v62, 1.0
	v_mul_f32_e32 v49, 0x3d372713, v61
	v_mul_f32_e32 v49, v61, v49
	v_fma_f32 v49, v61, v49, v61
	v_mul_f32_e32 v49, 0x3fcc422a, v49
	v_mul_f32_e32 v49, 0xbfb8aa3b, v49
	v_exp_f32_e32 v65, v49
	v_pk_mul_f32 v[34:35], v[34:35], v[62:63]
	v_pk_add_f32 v[62:63], v[64:65], 1.0 op_sel_hi:[1,0]
	s_nop 0
	v_div_scale_f32 v49, s[66:67], v63, v63, 1.0
	v_rcp_f32_e32 v64, v49
	v_cvt_pk_bf16_f32 v34, v34, v35
	v_fma_f32 v65, -v49, v64, 1.0
	v_fmac_f32_e32 v64, v65, v64
	v_div_scale_f32 v65, vcc, 1.0, v63, 1.0
	v_mul_f32_e32 v66, v65, v64
	v_fma_f32 v67, -v49, v66, v65
	v_fmac_f32_e32 v66, v67, v64
	v_fma_f32 v49, -v49, v66, v65
	v_div_fmas_f32 v49, v49, v64, v66
	v_div_fixup_f32 v63, v49, v63, 1.0
	v_div_scale_f32 v49, s[66:67], v62, v62, 1.0
	v_rcp_f32_e32 v64, v49
	s_nop 0
	v_fma_f32 v65, -v49, v64, 1.0
	v_fmac_f32_e32 v64, v65, v64
	v_div_scale_f32 v65, vcc, 1.0, v62, 1.0
	v_mul_f32_e32 v66, v65, v64
	v_fma_f32 v67, -v49, v66, v65
	v_fmac_f32_e32 v66, v67, v64
	v_fma_f32 v49, -v49, v66, v65
	v_div_fmas_f32 v49, v49, v64, v66
	v_div_fixup_f32 v62, v49, v62, 1.0
	v_mul_f32_e32 v49, 0x3d372713, v36
	v_mul_f32_e32 v49, v36, v49
	v_fma_f32 v49, v36, v49, v36
	v_mul_f32_e32 v49, 0x3fcc422a, v49
	v_mul_f32_e32 v49, 0xbfb8aa3b, v49
	v_pk_mul_f32 v[60:61], v[60:61], v[62:63]
	v_exp_f32_e32 v62, v49
	v_mul_f32_e32 v49, 0x3d372713, v40
	v_mul_f32_e32 v49, v40, v49
	v_fma_f32 v49, v40, v49, v40
	v_mul_f32_e32 v49, 0x3fcc422a, v49
	v_mul_f32_e32 v49, 0xbfb8aa3b, v49
	v_exp_f32_e32 v64, v49
	v_mul_f32_e32 v49, 0x3d372713, v37
	v_mul_f32_e32 v49, v37, v49
	v_fma_f32 v49, v37, v49, v37
	v_mul_f32_e32 v49, 0x3fcc422a, v49
	v_mul_f32_e32 v49, 0xbfb8aa3b, v49
	v_exp_f32_e32 v63, v49
	s_nop 0
	v_pk_add_f32 v[62:63], v[62:63], 1.0 op_sel_hi:[1,0]
	s_nop 0
	v_div_scale_f32 v49, s[66:67], v63, v63, 1.0
	v_rcp_f32_e32 v65, v49
	s_nop 0
	v_fma_f32 v66, -v49, v65, 1.0
	v_fmac_f32_e32 v65, v66, v65
	v_div_scale_f32 v66, vcc, 1.0, v63, 1.0
	v_mul_f32_e32 v67, v66, v65
	v_fma_f32 v68, -v49, v67, v66
	v_fmac_f32_e32 v67, v68, v65
	v_fma_f32 v49, -v49, v67, v66
	v_div_fmas_f32 v49, v49, v65, v67
	v_div_fixup_f32 v63, v49, v63, 1.0
	v_div_scale_f32 v49, s[66:67], v62, v62, 1.0
	v_rcp_f32_e32 v65, v49
	s_nop 0
	v_fma_f32 v66, -v49, v65, 1.0
	v_fmac_f32_e32 v65, v66, v65
	v_div_scale_f32 v66, vcc, 1.0, v62, 1.0
	v_mul_f32_e32 v67, v66, v65
	v_fma_f32 v68, -v49, v67, v66
	v_fmac_f32_e32 v67, v68, v65
	v_fma_f32 v49, -v49, v67, v66
	v_div_fmas_f32 v49, v49, v65, v67
	v_div_fixup_f32 v62, v49, v62, 1.0
	v_mul_f32_e32 v49, 0x3d372713, v41
	v_mul_f32_e32 v49, v41, v49
	v_fma_f32 v49, v41, v49, v41
	v_mul_f32_e32 v49, 0x3fcc422a, v49
	v_mul_f32_e32 v49, 0xbfb8aa3b, v49
	v_exp_f32_e32 v65, v49
	v_pk_mul_f32 v[36:37], v[36:37], v[62:63]
	v_pk_add_f32 v[62:63], v[64:65], 1.0 op_sel_hi:[1,0]
	s_nop 0
	v_div_scale_f32 v49, s[66:67], v63, v63, 1.0
	v_rcp_f32_e32 v64, v49
	v_cvt_pk_bf16_f32 v35, v36, v37
	v_cvt_pk_bf16_f32 v36, v60, v61
	v_fma_f32 v65, -v49, v64, 1.0
	v_fmac_f32_e32 v64, v65, v64
	v_div_scale_f32 v65, vcc, 1.0, v63, 1.0
	v_mul_f32_e32 v66, v65, v64
	v_fma_f32 v67, -v49, v66, v65
	v_fmac_f32_e32 v66, v67, v64
	v_fma_f32 v49, -v49, v66, v65
	v_div_fmas_f32 v49, v49, v64, v66
	v_div_fixup_f32 v63, v49, v63, 1.0
	v_div_scale_f32 v49, s[66:67], v62, v62, 1.0
	v_rcp_f32_e32 v64, v49
	s_nop 0
	v_fma_f32 v65, -v49, v64, 1.0
	v_fmac_f32_e32 v64, v65, v64
	v_div_scale_f32 v65, vcc, 1.0, v62, 1.0
	v_mul_f32_e32 v66, v65, v64
	v_fma_f32 v67, -v49, v66, v65
	v_fmac_f32_e32 v66, v67, v64
	v_fma_f32 v49, -v49, v66, v65
	v_div_fmas_f32 v49, v49, v64, v66
	v_div_fixup_f32 v62, v49, v62, 1.0
	v_pk_mul_f32 v[40:41], v[40:41], v[62:63]
	global_load_dwordx4 v[60:63], v[72:73], off offset:32
	v_cvt_pk_bf16_f32 v37, v40, v41
	global_load_dwordx4 v[38:41], v[38:39], off offset:32
	s_waitcnt vmcnt(1)
	v_mfma_f32_32x32x16_bf16 v[2:17], v[60:63], v[34:37], v[2:17]
	s_waitcnt vmcnt(0)
	v_mfma_f32_32x32x16_bf16 v[18:33], v[38:41], v[34:37], v[18:33]
	s_cbranch_scc0 .LBB0_1000
	v_lshlrev_b32_e32 v100, 4, v199
	s_cmp_eq_u32 s92, 0
	s_cbranch_scc1 .Lp8_w0
	s_add_i32 s96, s92, -1
	s_lshl_b32 s96, s96, 13
	v_add_u32_e32 v100, s96, v100
	s_nop 7
	s_nop 7
	ds_write_b128 v100, v[2:5]
	ds_write_b128 v100, v[6:9] offset:1024
	ds_write_b128 v100, v[10:13] offset:2048
	ds_write_b128 v100, v[14:17] offset:3072
	ds_write_b128 v100, v[18:21] offset:4096
	ds_write_b128 v100, v[22:25] offset:5120
	ds_write_b128 v100, v[26:29] offset:6144
	ds_write_b128 v100, v[30:33] offset:7168
	s_waitcnt lgkmcnt(0)
	s_barrier
	s_branch .LBB0_998
